# second merge pass (RWKV quarter): static priority raise for waves 4-7, as in the first merge pass
# baseline (speedup 1.0000x reference)
.LBB0_1169:
	s_or_b64 exec, exec, s[0:1]
	v_readlane_b32 s0, v252, 31
	v_mov_b32_e32 v2, v182
	v_readlane_b32 s1, v252, 32
	s_barrier
	s_andn2_b64 vcc, exec, s[0:1]
	v_readfirstlane_b32 s10, v2
	s_mov_b32 s53, 0x7ffffc00
	s_cbranch_vccnz .LBB0_1210
	s_cmp_lt_u32 s10, 0x100
	s_cbranch_scc1 .Lm4_prio_skip
	s_setprio 1
.Lm4_prio_skip:
	s_lshl_b32 s0, s10, 4
	s_ashr_i32 s18, s10, 7
	s_and_b32 s11, s10, 64
	s_and_b32 s19, s0, 0xfffffc00
	v_readlane_b32 s0, v252, 33
	v_readlane_b32 s52, v251, 16
	s_add_u32 s0, s48, s0
	v_readlane_b32 s56, v251, 20
	v_readlane_b32 s57, v251, 21
	s_addc_u32 s1, 0, 0
	v_readlane_b32 s58, v251, 22
	v_readlane_b32 s59, v251, 23
	v_readlane_b32 s60, v251, 24
	v_readlane_b32 s61, v251, 25
	v_readlane_b32 s62, v251, 26
	v_readlane_b32 s63, v251, 27
	v_readlane_b32 s64, v251, 28
	v_readlane_b32 s65, v251, 29
	v_readlane_b32 s66, v251, 30
	v_readlane_b32 s67, v251, 31
	s_mov_b64 s[20:21], s[56:57]
	s_lshl_b64 s[0:1], s[0:1], 11
	s_mov_b64 s[24:25], s[60:61]
	s_add_u32 s0, s24, s0
	s_addc_u32 s1, s25, s1
	s_add_u32 s8, s0, 0x400000
	s_addc_u32 s9, s1, 0
	s_add_u32 s4, s0, 0x400100
	s_addc_u32 s5, s1, 0
	s_add_u32 s6, s0, 0x400080
	s_addc_u32 s7, s1, 0
	s_add_u32 s0, s0, 0x400180
	v_readlane_b32 s2, v252, 35
	v_and_b32_e32 v1, 15, v2
	v_readlane_b32 s53, v251, 17
	v_readlane_b32 s54, v251, 18
	v_readlane_b32 s55, v251, 19
	s_addc_u32 s1, s1, 0
	s_add_i32 s12, s18, s2
	s_mov_b64 s[22:23], s[58:59]
	s_mov_b64 s[26:27], s[62:63]
	s_mov_b64 s[28:29], s[64:65]
	s_mov_b64 s[30:31], s[66:67]
	v_lshl_or_b32 v4, s12, 5, v1
	v_readlane_b32 s52, v253, 32
	v_ashrrev_i32_e32 v5, 31, v4
	v_readlane_b32 s53, v253, 33
	v_lshrrev_b32_e32 v3, 4, v2
	v_mov_b32_e32 v6, 0x2000
	v_lshl_add_u64 v[4:5], v[4:5], 2, s[52:53]
	global_load_dword v10, v[4:5], off
	global_load_dword v11, v[4:5], off offset:64
	global_load_dword v12, v[4:5], off offset:512
	global_load_dword v13, v[4:5], off offset:576
	v_bfe_u32 v50, v2, 4, 2
	v_lshrrev_b32_e32 v4, 1, v2
	v_bfe_u32 v5, v2, 1, 3
	v_lshl_add_u32 v6, v2, 4, v6
	v_ashrrev_i32_e32 v7, 3, v2
	v_xor_b32_e32 v2, v3, v2
	v_lshlrev_b32_e32 v2, 4, v2
	v_lshl_or_b32 v135, s18, 5, v1
	v_bitop3_b32 v4, v4, v50, 7 bitop3:0x6c
	v_bitop3_b32 v5, v50, v5, 4 bitop3:0x36
	v_or_b32_e32 v8, s11, v1
	v_ashrrev_i32_e32 v3, 7, v6
	v_and_b32_e32 v2, 0x70, v2
	v_readlane_b32 s2, v252, 42
	v_mov_b32_e32 v131, v0
	v_mov_b32_e32 v133, v0
	v_lshlrev_b32_e32 v51, 4, v4
	v_lshlrev_b32_e32 v53, 4, v5
	v_lshlrev_b32_e32 v4, 7, v135
	v_lshlrev_b32_e32 v5, 7, v8
	v_lshl_or_b32 v132, v3, 11, v2
	v_lshl_or_b32 v130, v7, 11, v2
	v_readlane_b32 s3, v252, 43
	v_or_b32_e32 v14, v4, v51
	v_or_b32_e32 v15, v53, v4
	v_or_b32_e32 v18, v51, v5
	v_or_b32_e32 v19, v53, v5
	v_lshl_or_b32 v134, v3, 9, v2
	v_lshl_or_b32 v136, v7, 9, v2
	v_lshl_add_u64 v[2:3], s[2:3], 0, v[130:131]
	v_lshl_add_u64 v[4:5], s[2:3], 0, v[132:133]
	s_mov_b64 s[12:13], 0x100
	v_lshl_add_u64 v[6:7], v[2:3], 0, s[70:71]
	v_lshl_add_u64 v[8:9], v[4:5], 0, s[70:71]
	v_lshl_add_u64 v[2:3], v[2:3], 0, s[12:13]
	v_lshl_add_u64 v[4:5], v[4:5], 0, s[12:13]
	s_and_b32 s12, s10, 0xffffff80
	s_add_i32 s12, s12, 0
	v_lshl_add_u32 v16, v1, 2, s12
	s_add_i32 s13, s19, 0
	v_add_u32_e32 v137, 0x24000, v16
	s_mov_b32 m0, s13
	v_add_u32_e32 v38, 0, v18
	v_add_u32_e32 v46, 0, v19
	v_readlane_b32 s60, v253, 40
	v_readlane_b32 s61, v253, 41
	v_lshlrev_b32_e32 v52, 3, v50
	s_waitcnt vmcnt(2)
	ds_write2_b32 v137, v10, v11 offset1:16
	s_waitcnt vmcnt(0)
	ds_write2_b32 v137, v12, v13 offset0:128 offset1:144
	global_load_lds_dwordx4 v130, s[2:3]
	s_add_i32 m0, s13, 0x2000
	v_mov_b32_e32 v50, 0
	global_load_lds_dwordx4 v132, s[2:3]
	v_readlane_b32 s2, v252, 36
	s_add_i32 m0, s13, 0x4000
	v_readlane_b32 s3, v252, 37
	v_readlane_b32 s39, v252, 34
	s_mov_b32 s20, 1
	s_mov_b32 s30, 3
	s_mov_b32 s21, 2
	v_or_b32_e32 v140, s11, v52
	global_load_lds_dwordx4 v130, s[2:3]
	s_add_i32 m0, s13, 0x6000
	v_lshl_add_u32 v141, v1, 7, 0
	global_load_lds_dwordx4 v132, s[2:3]
	s_add_i32 m0, s13, 0x8000
	v_readlane_b32 s2, v252, 38
	global_load_lds_dwordx4 v130, s[8:9]
	s_add_i32 m0, s13, 0xa000
	v_readlane_b32 s3, v252, 39
	global_load_lds_dwordx4 v132, s[8:9]
	s_add_i32 m0, s13, 0xc000
	v_readlane_b32 s8, v252, 44
	global_load_lds_dwordx4 v[6:7], off
	s_add_i32 m0, s13, 0xe000
	v_add_u32_e32 v6, 0, v14
	global_load_lds_dwordx4 v[8:9], off
	s_add_i32 m0, s13, 0x10000
	v_add_u32_e32 v14, 0, v15
	global_load_lds_dwordx4 v130, s[2:3]
	s_add_i32 m0, s13, 0x12000
	s_mov_b32 s34, 16
	global_load_lds_dwordx4 v132, s[2:3]
	s_add_i32 m0, s13, 0x14000
	v_readlane_b32 s2, v252, 40
	global_load_lds_dwordx4 v130, s[6:7]
	s_add_i32 m0, s13, 0x16000
	v_readlane_b32 s3, v252, 41
	global_load_lds_dwordx4 v132, s[6:7]
	s_add_i32 m0, s13, 0x18000
	s_mov_b32 s29, 0
	global_load_lds_dwordx4 v[2:3], off
	s_add_i32 m0, s13, 0x1a000
	v_mov_b32_e32 v154, 0
	global_load_lds_dwordx4 v[4:5], off
	s_add_i32 m0, s13, 0x1c000
	v_mov_b32_e32 v195, 0
	global_load_lds_dwordx4 v130, s[2:3]
	s_add_i32 m0, s13, 0x1e000
	v_mov_b32_e32 v156, 0
	global_load_lds_dwordx4 v132, s[2:3]
	s_add_i32 m0, s13, 0x20000
	v_mov_b32_e32 v157, 0
	global_load_lds_dwordx4 v130, s[4:5]
	s_add_i32 m0, s13, 0x22000
	v_mov_b32_e32 v158, 0
	global_load_lds_dwordx4 v132, s[4:5]
	s_waitcnt vmcnt(12)
	s_barrier
	ds_read_b128 v[2:5], v6
	ds_read_b128 v[6:9], v6 offset:2048
	ds_read_b128 v[10:13], v14
	ds_read_b128 v[14:17], v14 offset:2048
	ds_read_b128 v[18:21], v38 offset:32768
	ds_read_b128 v[26:29], v38 offset:34816
	ds_read_b128 v[22:25], v46 offset:32768
	ds_read_b128 v[30:33], v46 offset:34816
	ds_read_b128 v[34:37], v38 offset:36864
	ds_read_b128 v[38:41], v38 offset:38912
	ds_read_b128 v[42:45], v46 offset:36864
	ds_read_b128 v[46:49], v46 offset:38912
	s_lshl_b32 s4, s11, 1
	s_add_u32 s22, s60, s4
	s_addc_u32 s23, s61, 0
	s_lshl_b32 s4, s18, 12
	s_add_i32 s5, s4, 0xc000
	v_or_b32_e32 v142, s5, v51
	v_or_b32_e32 v144, s5, v53
	s_lshl_b32 s5, s10, 7
	s_add_i32 s6, s4, 0xc800
	s_and_b32 s5, s5, 0x2000
	v_or_b32_e32 v143, s6, v51
	v_or_b32_e32 v145, s6, v53
	s_or_b32 s6, s5, 0x14800
	s_or_b32 s7, s5, 0x15000
	s_or_b32 s5, s5, 0x14000
	v_or_b32_e32 v146, s6, v53
	v_or_b32_e32 v147, s7, v53
	v_or_b32_e32 v148, s5, v53
	v_or_b32_e32 v149, s6, v51
	v_or_b32_e32 v150, s7, v51
	s_add_i32 s24, s19, 0x2000
	v_or_b32_e32 v151, s5, v51
	v_or_b32_e32 v152, s4, v53
	v_or_b32_e32 v153, s4, v51
	s_add_i32 s25, s19, 0x8000
	s_add_i32 s26, s19, 0x4000
	s_add_i32 s27, s19, 0xa000
	s_add_i32 s28, s19, 0x6000
	s_mov_b64 s[10:11], -1
	s_mov_b64 s[4:5], 0
	v_mov_b32_e32 v159, 0
	v_mov_b32_e32 v160, 0
	v_mov_b32_e32 v161, 0
	v_mov_b32_e32 v166, 0
	v_mov_b32_e32 v167, 0
	v_mov_b32_e32 v168, 0
	v_mov_b32_e32 v169, 0
	v_mov_b32_e32 v170, 0
	v_mov_b32_e32 v171, 0
	v_mov_b32_e32 v172, 0
	v_mov_b32_e32 v173, 0
	v_mov_b32_e32 v174, 0
	v_mov_b32_e32 v175, 0
	v_mov_b32_e32 v176, 0
	v_mov_b32_e32 v177, 0
	v_mov_b32_e32 v178, 0
	v_mov_b32_e32 v179, 0
	v_mov_b32_e32 v180, 0
	v_mov_b32_e32 v181, 0
	v_mov_b32_e32 v197, 0
	v_mov_b32_e32 v198, 0
	v_mov_b32_e32 v199, 0
	v_mov_b32_e32 v200, 0
	v_mov_b32_e32 v201, 0
	v_mov_b32_e32 v202, 0
	v_mov_b32_e32 v203, 0
	v_mov_b32_e32 v204, 0
	v_mov_b32_e32 v206, 0
	v_mov_b32_e32 v205, 0
	v_mov_b32_e32 v208, 0
	v_mov_b32_e32 v207, 0
	v_mov_b32_e32 v210, 0
	v_mov_b32_e32 v209, 0
	v_mov_b32_e32 v212, 0
	v_mov_b32_e32 v211, 0
	v_mov_b32_e32 v214, 0
	v_mov_b32_e32 v213, 0
	v_mov_b32_e32 v216, 0
	v_mov_b32_e32 v215, 0
	v_mov_b32_e32 v218, 0
	v_mov_b32_e32 v217, 0
	v_mov_b32_e32 v220, 0
	v_mov_b32_e32 v219, 0
	v_mov_b32_e32 v222, 0
	v_mov_b32_e32 v221, 0
	v_mov_b32_e32 v224, 0
	v_mov_b32_e32 v223, 0
	v_mov_b32_e32 v226, 0
	v_mov_b32_e32 v225, 0
	v_mov_b32_e32 v228, 0
	v_mov_b32_e32 v227, 0
	v_mov_b32_e32 v230, 0
	v_mov_b32_e32 v229, 0
	v_mov_b32_e32 v232, 0
	v_mov_b32_e32 v231, 0
	v_mov_b32_e32 v234, 0
	v_mov_b32_e32 v233, 0
	v_mov_b32_e32 v236, 0
	v_mov_b32_e32 v235, 0
	v_lshlrev_b32_e32 v138, 1, v52
	s_mov_b32 s43, 0
	s_mov_b32 s31, s39
	s_mov_b32 s44, 0
	s_mov_b32 s17, 3
	s_mov_b32 s41, 0
	s_mov_b32 s42, 0
	s_mov_b32 s40, 0
	v_readlane_b32 s9, v252, 45
	s_mov_b64 s[14:15], 0
	s_mov_b32 s35, 0
	s_mov_b64 s[6:7], 0
	s_mov_b32 s37, 16
	s_mov_b32 s36, 0
	s_mov_b32 s38, 0
	v_mov_b32_e32 v51, v50
	v_mov_b32_e32 v52, v50
	v_mov_b32_e32 v53, v50
	v_mov_b32_e32 v54, v50
	v_mov_b32_e32 v55, v50
	v_mov_b32_e32 v56, v50
	v_mov_b32_e32 v57, v50
	v_mov_b32_e32 v58, v50
	v_mov_b32_e32 v59, v50
	v_mov_b32_e32 v60, v50
	v_mov_b32_e32 v61, v50
	v_mov_b32_e32 v62, v50
	v_mov_b32_e32 v63, v50
	v_mov_b32_e32 v64, v50
	v_mov_b32_e32 v65, v50
	v_mov_b32_e32 v66, v50
	v_mov_b32_e32 v67, v50
	v_mov_b32_e32 v68, v50
	v_mov_b32_e32 v69, v50
	v_mov_b32_e32 v70, v50
	v_mov_b32_e32 v71, v50
	v_mov_b32_e32 v72, v50
	v_mov_b32_e32 v73, v50
	v_mov_b32_e32 v74, v50
	v_mov_b32_e32 v75, v50
	v_mov_b32_e32 v76, v50
	v_mov_b32_e32 v77, v50
	v_mov_b32_e32 v78, v50
	v_mov_b32_e32 v79, v50
	v_mov_b32_e32 v80, v50
	v_mov_b32_e32 v81, v50
	v_mov_b32_e32 v82, v50
	v_mov_b32_e32 v83, v50
	v_mov_b32_e32 v84, v50
	v_mov_b32_e32 v85, v50
	v_mov_b32_e32 v86, v50
	v_mov_b32_e32 v87, v50
	v_mov_b32_e32 v88, v50
	v_mov_b32_e32 v89, v50
	v_mov_b32_e32 v90, v50
	v_mov_b32_e32 v91, v50
	v_mov_b32_e32 v92, v50
	v_mov_b32_e32 v93, v50
	v_mov_b32_e32 v94, v50
	v_mov_b32_e32 v95, v50
	v_mov_b32_e32 v96, v50
	v_mov_b32_e32 v97, v50
	v_mov_b32_e32 v98, v50
	v_mov_b32_e32 v99, v50
	v_mov_b32_e32 v100, v50
	v_mov_b32_e32 v101, v50
	v_mov_b32_e32 v102, v50
	v_mov_b32_e32 v103, v50
	v_mov_b32_e32 v104, v50
	v_mov_b32_e32 v105, v50
	v_mov_b32_e32 v106, v50
	v_mov_b32_e32 v107, v50
	v_mov_b32_e32 v108, v50
	v_mov_b32_e32 v109, v50
	v_mov_b32_e32 v110, v50
	v_mov_b32_e32 v111, v50
	v_mov_b32_e32 v112, v50
	v_mov_b32_e32 v113, v50
	v_readlane_b32 s54, v253, 34
	v_readlane_b32 s55, v253, 35
	v_readlane_b32 s56, v253, 36
	v_readlane_b32 s57, v253, 37
	v_readlane_b32 s58, v253, 38
	v_readlane_b32 s59, v253, 39
	v_readlane_b32 s62, v253, 42
	v_readlane_b32 s63, v253, 43
	v_readlane_b32 s64, v253, 44
	v_readlane_b32 s65, v253, 45
	v_readlane_b32 s66, v253, 46
	v_readlane_b32 s67, v253, 47
	s_branch .LBB0_1173

.LBB0_1210:
	s_setprio 0
	s_waitcnt vmcnt(0)
	v_readlane_b32 s0, v253, 25
	s_movk_i32 s52, 0x277
	s_add_i32 s16, s0, 2
	s_waitcnt vmcnt(0) lgkmcnt(0)
	s_barrier
	s_mov_b64 s[0:1], exec
	v_readlane_b32 s2, v253, 26
	v_readlane_b32 s3, v253, 27
	v_readlane_b32 s56, v253, 32
	s_and_b64 s[2:3], s[0:1], s[2:3]
	v_readlane_b32 s57, v253, 33
	v_readlane_b32 s58, v253, 34
	v_readlane_b32 s59, v253, 35
	v_readlane_b32 s60, v253, 36
	v_readlane_b32 s61, v253, 37
	v_readlane_b32 s62, v253, 38
	v_readlane_b32 s63, v253, 39
	v_readlane_b32 s64, v253, 40
	v_readlane_b32 s65, v253, 41
	v_readlane_b32 s66, v253, 42
	v_readlane_b32 s67, v253, 43
	v_readlane_b32 s68, v253, 44
	v_readlane_b32 s69, v253, 45
	v_readlane_b32 s70, v253, 46
	v_readlane_b32 s71, v253, 47
	s_mov_b64 exec, s[2:3]
	s_cbranch_execz .LBB0_1216
	s_mov_b64 s[2:3], exec
	buffer_wbl2 sc1
	s_waitcnt vmcnt(0)
	v_mbcnt_lo_u32_b32 v1, s2, 0
	v_mbcnt_hi_u32_b32 v1, s3, v1
	v_cmp_eq_u32_e32 vcc, 0, v1
	s_and_saveexec_b64 s[4:5], vcc
	s_cbranch_execz .LBB0_1213
	s_bcnt1_i32_b64 s2, s[2:3]
	v_mov_b32_e32 v1, s2
	global_atomic_add v0, v1, s[68:69] offset:128
